# attention steady loop trims round 2: vacuous lgkmcnt waits before QK MFMAs removed, one counted wait per two PV MFMAs, sacc+0 folded, resc flag copy, rescale address add moved to rare path
# speedup vs baseline: 1.0016x; 1.0016x over previous
.LBB0_310:
	s_lshl_b32 s14, s14, 1
	v_add_u32_e32 v217, s14, v244
	ds_read_b64_tr_b16 v[208:209], v217 offset:24576
	ds_read_b64_tr_b16 v[210:211], v217 offset:25088
	v_mfma_f32_32x32x16_bf16 v[128:143], v[204:207], v[172:175], v[64:79]
	v_add_f32_e32 v112, v96, v97
	v_add_f32_e32 v112, v98, v112
	v_add_f32_e32 v112, v99, v112
	v_add_f32_e32 v112, v100, v112
	v_add_f32_e32 v112, v101, v112
	v_cvt_pk_bf16_f32 v164, v96, v97
	v_cvt_pk_bf16_f32 v165, v98, v99
	ds_read_b64_tr_b16 v[96:97], v217 offset:28672
	ds_read_b64_tr_b16 v[98:99], v217 offset:29184
	v_add_f32_e32 v112, v102, v112
	v_add_f32_e32 v112, v103, v112
	v_add_f32_e32 v112, v104, v112
	v_add_f32_e32 v144, v105, v112
	v_mfma_f32_32x32x16_bf16 v[112:127], v[200:203], v[172:175], v[64:79]
	v_cvt_pk_bf16_f32 v166, v100, v101
	v_cvt_pk_bf16_f32 v167, v102, v103
	ds_read_b64_tr_b16 v[100:101], v217 offset:25600
	ds_read_b64_tr_b16 v[102:103], v217 offset:26112
	v_mfma_f32_32x32x16_bf16 v[128:143], v[196:199], v[168:171], v[128:143]
	v_add_f32_e32 v144, v106, v144
	v_add_f32_e32 v144, v107, v144
	v_add_f32_e32 v144, v108, v144
	v_add_f32_e32 v144, v109, v144
	v_cvt_pk_bf16_f32 v156, v104, v105
	v_cvt_pk_bf16_f32 v157, v106, v107
	ds_read_b64_tr_b16 v[104:105], v217 offset:29696
	ds_read_b64_tr_b16 v[106:107], v217 offset:30208
	v_mfma_f32_32x32x16_bf16 v[112:127], v[192:195], v[168:171], v[112:127]
	v_add_f32_e32 v144, v110, v144
	v_add_f32_e32 v144, v111, v144
	v_add_f32_e32 v144, v80, v144
	v_add_f32_e32 v144, v81, v144
	v_cvt_pk_bf16_f32 v158, v108, v109
	v_cvt_pk_bf16_f32 v159, v110, v111
	ds_read_b64_tr_b16 v[108:109], v217 offset:26624
	ds_read_b64_tr_b16 v[110:111], v217 offset:27136
	v_mfma_f32_32x32x16_bf16 v[128:143], v[188:191], v[160:163], v[128:143]
	v_add_f32_e32 v144, v82, v144
	v_add_f32_e32 v144, v83, v144
	v_add_f32_e32 v144, v84, v144
	v_add_f32_e32 v144, v85, v144
	v_cvt_pk_bf16_f32 v148, v80, v81
	v_cvt_pk_bf16_f32 v149, v82, v83
	ds_read_b64_tr_b16 v[80:81], v217 offset:30720
	ds_read_b64_tr_b16 v[82:83], v217 offset:31232
	v_mfma_f32_32x32x16_bf16 v[112:127], v[184:187], v[160:163], v[112:127]
	v_add_f32_e32 v144, v86, v144
	v_add_f32_e32 v144, v87, v144
	v_add_f32_e32 v144, v88, v144
	v_add_f32_e32 v144, v89, v144
	v_cvt_pk_bf16_f32 v150, v84, v85
	v_cvt_pk_bf16_f32 v151, v86, v87
	ds_read_b64_tr_b16 v[84:85], v217 offset:27648
	ds_read_b64_tr_b16 v[86:87], v217 offset:28160
	v_mfma_f32_32x32x16_bf16 v[128:143], v[180:183], v[152:155], v[128:143]
	v_add_f32_e32 v144, v90, v144
	v_add_f32_e32 v144, v91, v144
	v_add_f32_e32 v144, v92, v144
	v_add_f32_e32 v180, v93, v144
	v_cvt_pk_bf16_f32 v144, v88, v89
	v_cvt_pk_bf16_f32 v145, v90, v91
	ds_read_b64_tr_b16 v[88:89], v217 offset:31744
	ds_read_b64_tr_b16 v[90:91], v217 offset:32256
	v_mfma_f32_32x32x16_bf16 v[112:127], v[176:179], v[152:155], v[112:127]
	v_add_f32_e32 v146, v94, v180
	v_add_f32_e32 v176, v95, v146
	v_cvt_pk_bf16_f32 v146, v92, v93
	v_cvt_pk_bf16_f32 v147, v94, v95
	v_lshl_add_u64 v[224:225], v[220:221], 0, s[30:31]
	s_mov_b64 s[14:15], 0x48080000
	s_add_i32 m0, s24, s63
	v_lshl_add_u64 v[92:93], v[224:225], 0, s[14:15]
	global_load_lds_dwordx4 v[92:93], off
	v_lshl_add_u64 v[222:223], v[218:219], 0, s[30:31]
	s_mov_b64 s[14:15], 0x4c040000
	v_lshl_add_u64 v[92:93], v[222:223], 0, s[14:15]
	s_lshl_b32 s14, s22, 1
	s_add_i32 s14, s14, s64
	s_mov_b32 m0, s14
	s_mov_b64 s[20:21], 0x4c040080
	global_load_lds_dwordx4 v[92:93], off
	s_add_i32 m0, s14, 0x2000
	v_lshl_add_u64 v[92:93], v[222:223], 0, s[20:21]
	global_load_lds_dwordx4 v[92:93], off
	v_max_f32_e32 v92, v128, v129
	v_max3_f32 v93, v130, v131, v113
	v_max3_f32 v92, v92, v112, v114
	v_max3_f32 v92, v92, v115, v132
	v_max3_f32 v93, v93, v134, v135
	v_max3_f32 v92, v92, v133, v116
	v_max3_f32 v93, v93, v118, v119
	v_max3_f32 v92, v92, v117, v136
	v_max3_f32 v93, v93, v138, v139
	v_max3_f32 v92, v92, v137, v120
	v_max3_f32 v93, v93, v122, v123
	v_max3_f32 v92, v92, v121, v140
	v_max3_f32 v93, v93, v142, v143
	v_max3_f32 v92, v92, v141, v124
	v_max3_f32 v93, v93, v126, v127
	v_max3_f32 v92, v92, v125, v93
	v_mov_b32_e32 v93, v92
	s_nop 1
	v_permlane32_swap_b32_e32 v92, v93
	v_max_f32_e32 v92, v92, v93
	v_cmp_lt_f32_e32 vcc, s33, v92
	v_add_f32_e32 v215, v249, v176
	s_mov_b64 s[20:21], vcc
	s_cbranch_vccnz .LBB0_318
.LBB0_311:
	s_waitcnt lgkmcnt(12)
	v_mfma_f32_32x32x16_bf16 v[32:47], v[164:167], v[208:211], v[32:47]
	v_exp_f32_e32 v128, v128
	v_exp_f32_e32 v129, v129
	ds_read_b64_tr_b16 v[92:93], v217 offset:32768
	ds_read_b64_tr_b16 v[94:95], v217 offset:33280
	v_mfma_f32_32x32x16_bf16 v[48:63], v[164:167], v[96:99], v[48:63]
	v_exp_f32_e32 v130, v130
	v_exp_f32_e32 v131, v131
	ds_read_b64_tr_b16 v[96:97], v217 offset:36864
	ds_read_b64_tr_b16 v[98:99], v217 offset:37376
	s_waitcnt lgkmcnt(12)
	v_mfma_f32_32x32x16_bf16 v[32:47], v[156:159], v[100:103], v[32:47]
	v_exp_f32_e32 v132, v132
	v_exp_f32_e32 v133, v133
	ds_read_b64_tr_b16 v[100:101], v217 offset:33792
	ds_read_b64_tr_b16 v[102:103], v217 offset:34304
	v_mfma_f32_32x32x16_bf16 v[48:63], v[156:159], v[104:107], v[48:63]
	v_exp_f32_e32 v134, v134
	v_exp_f32_e32 v135, v135
	ds_read_b64_tr_b16 v[104:105], v217 offset:37888
	ds_read_b64_tr_b16 v[106:107], v217 offset:38400
	s_waitcnt lgkmcnt(12)
	v_mfma_f32_32x32x16_bf16 v[32:47], v[148:151], v[108:111], v[32:47]
	v_exp_f32_e32 v136, v136
	v_exp_f32_e32 v137, v137
	ds_read_b64_tr_b16 v[108:109], v217 offset:34816
	ds_read_b64_tr_b16 v[110:111], v217 offset:35328
	v_mfma_f32_32x32x16_bf16 v[48:63], v[148:151], v[80:83], v[48:63]
	v_exp_f32_e32 v138, v138
	v_exp_f32_e32 v139, v139
	ds_read_b64_tr_b16 v[188:189], v217 offset:38912
	ds_read_b64_tr_b16 v[190:191], v217 offset:39424
	s_waitcnt lgkmcnt(12)
	v_mfma_f32_32x32x16_bf16 v[32:47], v[144:147], v[84:87], v[32:47]
	v_exp_f32_e32 v140, v140
	v_exp_f32_e32 v141, v141
	ds_read_b64_tr_b16 v[84:85], v217 offset:35840
	ds_read_b64_tr_b16 v[86:87], v217 offset:36352
	v_mfma_f32_32x32x16_bf16 v[48:63], v[144:147], v[88:91], v[48:63]
	v_exp_f32_e32 v142, v142
	v_exp_f32_e32 v143, v143
	ds_read_b64_tr_b16 v[88:89], v217 offset:39936
	ds_read_b64_tr_b16 v[90:91], v217 offset:40448
	s_waitcnt lgkmcnt(12)
	v_mfma_f32_32x32x16_bf16 v[16:31], v[164:167], v[92:95], v[16:31]
	v_exp_f32_e32 v112, v112
	v_exp_f32_e32 v113, v113
	v_add_u32_e32 v92, s22, v247
	ds_read_b128 v[80:83], v92
	ds_read_b128 v[200:203], v92 offset:512
	v_mfma_f32_32x32x16_bf16 v[0:15], v[164:167], v[96:99], v[0:15]
	v_exp_f32_e32 v114, v114
	v_exp_f32_e32 v115, v115
	ds_read_b128 v[204:207], v92 offset:2048
	ds_read_b128 v[196:199], v92 offset:2560
	s_waitcnt lgkmcnt(12)
	v_mfma_f32_32x32x16_bf16 v[16:31], v[156:159], v[100:103], v[16:31]
	v_exp_f32_e32 v116, v116
	v_exp_f32_e32 v117, v117
	ds_read_b128 v[192:195], v92 offset:4096
	ds_read_b128 v[184:187], v92 offset:4608
	v_mfma_f32_32x32x16_bf16 v[0:15], v[156:159], v[104:107], v[0:15]
	v_exp_f32_e32 v118, v118
	v_exp_f32_e32 v119, v119
	ds_read_b128 v[180:183], v92 offset:6144
	ds_read_b128 v[176:179], v92 offset:6656
	s_waitcnt lgkmcnt(12)
	v_mfma_f32_32x32x16_bf16 v[16:31], v[148:151], v[108:111], v[16:31]
	v_exp_f32_e32 v120, v120
	v_exp_f32_e32 v121, v121
	v_mfma_f32_32x32x16_bf16 v[0:15], v[148:151], v[188:191], v[0:15]
	v_exp_f32_e32 v122, v122
	v_exp_f32_e32 v123, v123
	s_waitcnt lgkmcnt(8)
	v_mfma_f32_32x32x16_bf16 v[16:31], v[144:147], v[84:87], v[16:31]
	v_exp_f32_e32 v124, v124
	v_exp_f32_e32 v125, v125
	v_mfma_f32_32x32x16_bf16 v[0:15], v[144:147], v[88:91], v[0:15]
	v_exp_f32_e32 v126, v126
	v_exp_f32_e32 v127, v127
	s_waitcnt vmcnt(3) lgkmcnt(0)
	s_barrier
	s_cmp_eq_u64 s[20:21], 0
	s_cbranch_scc1 .LBB0_313
	s_waitcnt lgkmcnt(0)
	v_add_u32_e32 v208, s65, v248
	ds_read_b128 v[84:87], v208 offset:96
	ds_read_b128 v[88:91], v208 offset:64
	ds_read_b128 v[92:95], v208 offset:32
	ds_read_b128 v[96:99], v208
	s_waitcnt lgkmcnt(3)
	v_pk_mul_f32 v[44:45], v[44:45], v[84:85]
	s_waitcnt lgkmcnt(2)
	v_pk_mul_f32 v[40:41], v[40:41], v[88:89]
	s_waitcnt lgkmcnt(1)
	v_pk_mul_f32 v[36:37], v[36:37], v[92:93]
	v_pk_mul_f32 v[46:47], v[46:47], v[86:87]
	v_pk_mul_f32 v[42:43], v[42:43], v[90:91]
	v_pk_mul_f32 v[38:39], v[38:39], v[94:95]
	s_waitcnt lgkmcnt(0)
	v_pk_mul_f32 v[34:35], v[34:35], v[98:99]
	v_pk_mul_f32 v[32:33], v[32:33], v[96:97]
	v_pk_mul_f32 v[60:61], v[60:61], v[84:85]
	v_pk_mul_f32 v[56:57], v[56:57], v[88:89]
	v_pk_mul_f32 v[52:53], v[52:53], v[92:93]
	v_pk_mul_f32 v[62:63], v[62:63], v[86:87]
	v_pk_mul_f32 v[58:59], v[58:59], v[90:91]
	v_pk_mul_f32 v[54:55], v[54:55], v[94:95]
	v_pk_mul_f32 v[50:51], v[50:51], v[98:99]
	v_pk_mul_f32 v[48:49], v[48:49], v[96:97]
	v_pk_mul_f32 v[28:29], v[28:29], v[84:85]
	v_pk_mul_f32 v[24:25], v[24:25], v[88:89]
	v_pk_mul_f32 v[20:21], v[20:21], v[92:93]
	v_pk_mul_f32 v[30:31], v[30:31], v[86:87]
	v_pk_mul_f32 v[26:27], v[26:27], v[90:91]
	v_pk_mul_f32 v[22:23], v[22:23], v[94:95]
	v_pk_mul_f32 v[18:19], v[18:19], v[98:99]
	v_pk_mul_f32 v[16:17], v[16:17], v[96:97]
	v_pk_mul_f32 v[12:13], v[12:13], v[84:85]
	v_pk_mul_f32 v[8:9], v[8:9], v[88:89]
	v_pk_mul_f32 v[4:5], v[4:5], v[92:93]
	v_pk_mul_f32 v[14:15], v[14:15], v[86:87]
	v_pk_mul_f32 v[10:11], v[10:11], v[90:91]
	v_pk_mul_f32 v[6:7], v[6:7], v[94:95]
	v_pk_mul_f32 v[2:3], v[2:3], v[98:99]
	v_pk_mul_f32 v[0:1], v[0:1], v[96:97]
.LBB0_313:
	s_add_i32 s14, s22, 0x2000
	s_cmpk_lg_i32 s22, 0x4000
	s_cselect_b32 s66, s14, 0
	s_lshl_b32 s14, s24, 1
	v_add_u32_e32 v209, s14, v244
	ds_read_b64_tr_b16 v[188:189], v209 offset:24576
	ds_read_b64_tr_b16 v[190:191], v209 offset:25088
	v_mfma_f32_32x32x16_bf16 v[96:111], v[80:83], v[172:175], v[64:79]
	v_add_f32_e32 v84, v128, v129
	v_add_f32_e32 v84, v130, v84
	v_add_f32_e32 v84, v131, v84
	v_add_f32_e32 v84, v132, v84
	v_add_f32_e32 v84, v133, v84
	v_cvt_pk_bf16_f32 v164, v128, v129
	v_cvt_pk_bf16_f32 v165, v130, v131
	ds_read_b64_tr_b16 v[128:129], v209 offset:28672
	ds_read_b64_tr_b16 v[130:131], v209 offset:29184
	v_add_f32_e32 v80, v134, v84
	v_add_f32_e32 v80, v135, v80
	v_add_f32_e32 v80, v136, v80
	v_add_f32_e32 v144, v137, v80
	v_mfma_f32_32x32x16_bf16 v[80:95], v[200:203], v[172:175], v[64:79]
	v_cvt_pk_bf16_f32 v166, v132, v133
	v_cvt_pk_bf16_f32 v167, v134, v135
	ds_read_b64_tr_b16 v[132:133], v209 offset:25600
	ds_read_b64_tr_b16 v[134:135], v209 offset:26112
	v_mfma_f32_32x32x16_bf16 v[96:111], v[204:207], v[168:171], v[96:111]
	v_add_f32_e32 v144, v138, v144
	v_add_f32_e32 v144, v139, v144
	v_add_f32_e32 v144, v140, v144
	v_add_f32_e32 v144, v141, v144
	v_cvt_pk_bf16_f32 v156, v136, v137
	v_cvt_pk_bf16_f32 v157, v138, v139
	ds_read_b64_tr_b16 v[136:137], v209 offset:29696
	ds_read_b64_tr_b16 v[138:139], v209 offset:30208
	v_mfma_f32_32x32x16_bf16 v[80:95], v[196:199], v[168:171], v[80:95]
	v_add_f32_e32 v144, v142, v144
	v_add_f32_e32 v144, v143, v144
	v_add_f32_e32 v144, v112, v144
	v_add_f32_e32 v144, v113, v144
	v_cvt_pk_bf16_f32 v158, v140, v141
	v_cvt_pk_bf16_f32 v159, v142, v143
	ds_read_b64_tr_b16 v[140:141], v209 offset:26624
	ds_read_b64_tr_b16 v[142:143], v209 offset:27136
	v_mfma_f32_32x32x16_bf16 v[96:111], v[192:195], v[160:163], v[96:111]
	v_add_f32_e32 v144, v114, v144
	v_add_f32_e32 v144, v115, v144
	v_add_f32_e32 v144, v116, v144
	v_add_f32_e32 v144, v117, v144
	v_cvt_pk_bf16_f32 v148, v112, v113
	v_cvt_pk_bf16_f32 v149, v114, v115
	ds_read_b64_tr_b16 v[112:113], v209 offset:30720
	ds_read_b64_tr_b16 v[114:115], v209 offset:31232
	v_mfma_f32_32x32x16_bf16 v[80:95], v[184:187], v[160:163], v[80:95]
	v_add_f32_e32 v144, v118, v144
	v_add_f32_e32 v144, v119, v144
	v_add_f32_e32 v144, v120, v144
	v_add_f32_e32 v144, v121, v144
	v_cvt_pk_bf16_f32 v150, v116, v117
	v_cvt_pk_bf16_f32 v151, v118, v119
	ds_read_b64_tr_b16 v[116:117], v209 offset:27648
	ds_read_b64_tr_b16 v[118:119], v209 offset:28160
	v_mfma_f32_32x32x16_bf16 v[96:111], v[180:183], v[152:155], v[96:111]
	v_add_f32_e32 v144, v122, v144
	v_add_f32_e32 v144, v123, v144
	v_add_f32_e32 v144, v124, v144
	v_add_f32_e32 v180, v125, v144
	v_cvt_pk_bf16_f32 v144, v120, v121
	v_cvt_pk_bf16_f32 v145, v122, v123
	ds_read_b64_tr_b16 v[120:121], v209 offset:31744
	ds_read_b64_tr_b16 v[122:123], v209 offset:32256
	v_mfma_f32_32x32x16_bf16 v[80:95], v[176:179], v[152:155], v[80:95]
	v_add_f32_e32 v146, v126, v180
	v_add_f32_e32 v176, v127, v146
	v_cvt_pk_bf16_f32 v146, v124, v125
	v_cvt_pk_bf16_f32 v147, v126, v127
	s_mov_b64 s[14:15], 0x480a0000
	s_add_i32 m0, s22, s63
	v_lshl_add_u64 v[124:125], v[224:225], 0, s[14:15]
	global_load_lds_dwordx4 v[124:125], off
	s_mov_b64 s[14:15], 0x4c060000
	v_lshl_add_u64 v[124:125], v[222:223], 0, s[14:15]
	s_lshl_b32 s14, s66, 1
	s_add_i32 s20, s14, s64
	s_mov_b32 m0, s20
	s_mov_b64 s[14:15], 0x4c060080
	global_load_lds_dwordx4 v[124:125], off
	s_add_i32 m0, s20, 0x2000
	v_lshl_add_u64 v[124:125], v[222:223], 0, s[14:15]
	global_load_lds_dwordx4 v[124:125], off
	v_max_f32_e32 v124, v96, v97
	v_max3_f32 v125, v98, v99, v81
	v_max3_f32 v124, v124, v80, v82
	v_max3_f32 v124, v124, v83, v100
	v_max3_f32 v125, v125, v102, v103
	v_max3_f32 v124, v124, v101, v84
	v_max3_f32 v125, v125, v86, v87
	v_max3_f32 v124, v124, v85, v104
	v_max3_f32 v125, v125, v106, v107
	v_max3_f32 v124, v124, v105, v88
	v_max3_f32 v125, v125, v90, v91
	v_max3_f32 v124, v124, v89, v108
	v_max3_f32 v125, v125, v110, v111
	v_max3_f32 v124, v124, v109, v92
	v_max3_f32 v125, v125, v94, v95
	v_max3_f32 v124, v124, v93, v125
	v_mov_b32_e32 v125, v124
	s_nop 1
	v_permlane32_swap_b32_e32 v124, v125
	v_max_f32_e32 v124, v124, v125
	v_cmp_lt_f32_e32 vcc, s33, v124
	v_add_f32_e32 v249, v215, v176
	s_mov_b64 s[20:21], vcc
	s_cbranch_vccnz .LBB0_321
.LBB0_314:
	s_waitcnt lgkmcnt(12)
	v_mfma_f32_32x32x16_bf16 v[32:47], v[164:167], v[188:191], v[32:47]
	v_exp_f32_e32 v96, v96
	v_exp_f32_e32 v97, v97
	ds_read_b64_tr_b16 v[124:125], v209 offset:32768
	ds_read_b64_tr_b16 v[126:127], v209 offset:33280
	v_mfma_f32_32x32x16_bf16 v[48:63], v[164:167], v[128:131], v[48:63]
	v_exp_f32_e32 v98, v98
	v_exp_f32_e32 v99, v99
	ds_read_b64_tr_b16 v[128:129], v209 offset:36864
	ds_read_b64_tr_b16 v[130:131], v209 offset:37376
	s_waitcnt lgkmcnt(12)
	v_mfma_f32_32x32x16_bf16 v[32:47], v[156:159], v[132:135], v[32:47]
	v_exp_f32_e32 v100, v100
	v_exp_f32_e32 v101, v101
	ds_read_b64_tr_b16 v[132:133], v209 offset:33792
	ds_read_b64_tr_b16 v[134:135], v209 offset:34304
	v_mfma_f32_32x32x16_bf16 v[48:63], v[156:159], v[136:139], v[48:63]
	v_exp_f32_e32 v102, v102
	v_exp_f32_e32 v103, v103
	ds_read_b64_tr_b16 v[136:137], v209 offset:37888
	ds_read_b64_tr_b16 v[138:139], v209 offset:38400
	s_waitcnt lgkmcnt(12)
	v_mfma_f32_32x32x16_bf16 v[32:47], v[148:151], v[140:143], v[32:47]
	v_exp_f32_e32 v104, v104
	v_exp_f32_e32 v105, v105
	ds_read_b64_tr_b16 v[140:141], v209 offset:34816
	ds_read_b64_tr_b16 v[142:143], v209 offset:35328
	v_mfma_f32_32x32x16_bf16 v[48:63], v[148:151], v[112:115], v[48:63]
	v_exp_f32_e32 v106, v106
	v_exp_f32_e32 v107, v107
	ds_read_b64_tr_b16 v[112:113], v209 offset:38912
	ds_read_b64_tr_b16 v[114:115], v209 offset:39424
	s_waitcnt lgkmcnt(12)
	v_mfma_f32_32x32x16_bf16 v[32:47], v[144:147], v[116:119], v[32:47]
	v_exp_f32_e32 v108, v108
	v_exp_f32_e32 v109, v109
	ds_read_b64_tr_b16 v[116:117], v209 offset:35840
	ds_read_b64_tr_b16 v[118:119], v209 offset:36352
	v_mfma_f32_32x32x16_bf16 v[48:63], v[144:147], v[120:123], v[48:63]
	v_exp_f32_e32 v110, v110
	v_exp_f32_e32 v111, v111
	ds_read_b64_tr_b16 v[120:121], v209 offset:39936
	ds_read_b64_tr_b16 v[122:123], v209 offset:40448
	s_waitcnt lgkmcnt(12)
	v_mfma_f32_32x32x16_bf16 v[16:31], v[164:167], v[124:127], v[16:31]
	v_exp_f32_e32 v80, v80
	v_exp_f32_e32 v81, v81
	v_add_u32_e32 v124, s66, v247
	ds_read_b128 v[204:207], v124
	ds_read_b128 v[200:203], v124 offset:512
	v_mfma_f32_32x32x16_bf16 v[0:15], v[164:167], v[128:131], v[0:15]
	v_exp_f32_e32 v82, v82
	v_exp_f32_e32 v83, v83
	ds_read_b128 v[196:199], v124 offset:2048
	ds_read_b128 v[192:195], v124 offset:2560
	s_waitcnt lgkmcnt(12)
	v_mfma_f32_32x32x16_bf16 v[16:31], v[156:159], v[132:135], v[16:31]
	v_exp_f32_e32 v84, v84
	v_exp_f32_e32 v85, v85
	ds_read_b128 v[188:191], v124 offset:4096
	ds_read_b128 v[184:187], v124 offset:4608
	v_mfma_f32_32x32x16_bf16 v[0:15], v[156:159], v[136:139], v[0:15]
	v_exp_f32_e32 v86, v86
	v_exp_f32_e32 v87, v87
	ds_read_b128 v[180:183], v124 offset:6144
	ds_read_b128 v[176:179], v124 offset:6656
	s_waitcnt lgkmcnt(12)
	v_mfma_f32_32x32x16_bf16 v[16:31], v[148:151], v[140:143], v[16:31]
	v_exp_f32_e32 v88, v88
	v_exp_f32_e32 v89, v89
	v_mfma_f32_32x32x16_bf16 v[0:15], v[148:151], v[112:115], v[0:15]
	v_exp_f32_e32 v90, v90
	v_exp_f32_e32 v91, v91
	s_waitcnt lgkmcnt(8)
	v_mfma_f32_32x32x16_bf16 v[16:31], v[144:147], v[116:119], v[16:31]
	v_exp_f32_e32 v92, v92
	v_exp_f32_e32 v93, v93
	v_mfma_f32_32x32x16_bf16 v[0:15], v[144:147], v[120:123], v[0:15]
	v_exp_f32_e32 v94, v94
	v_exp_f32_e32 v95, v95
	s_waitcnt vmcnt(3) lgkmcnt(0)
	s_barrier
	s_cmp_eq_u64 s[20:21], 0
	s_cbranch_scc1 .LBB0_316
	s_waitcnt lgkmcnt(0)
	v_add_u32_e32 v208, s65, v248
	ds_read_b128 v[112:115], v208 offset:96
	ds_read_b128 v[116:119], v208 offset:64
	ds_read_b128 v[120:123], v208 offset:32
	ds_read_b128 v[124:127], v208
	s_waitcnt lgkmcnt(3)
	v_pk_mul_f32 v[44:45], v[44:45], v[112:113]
	s_waitcnt lgkmcnt(2)
	v_pk_mul_f32 v[40:41], v[40:41], v[116:117]
	s_waitcnt lgkmcnt(1)
	v_pk_mul_f32 v[36:37], v[36:37], v[120:121]
	v_pk_mul_f32 v[46:47], v[46:47], v[114:115]
	v_pk_mul_f32 v[42:43], v[42:43], v[118:119]
	v_pk_mul_f32 v[38:39], v[38:39], v[122:123]
	s_waitcnt lgkmcnt(0)
	v_pk_mul_f32 v[34:35], v[34:35], v[126:127]
	v_pk_mul_f32 v[32:33], v[32:33], v[124:125]
	v_pk_mul_f32 v[60:61], v[60:61], v[112:113]
	v_pk_mul_f32 v[56:57], v[56:57], v[116:117]
	v_pk_mul_f32 v[52:53], v[52:53], v[120:121]
	v_pk_mul_f32 v[62:63], v[62:63], v[114:115]
	v_pk_mul_f32 v[58:59], v[58:59], v[118:119]
	v_pk_mul_f32 v[54:55], v[54:55], v[122:123]
	v_pk_mul_f32 v[50:51], v[50:51], v[126:127]
	v_pk_mul_f32 v[48:49], v[48:49], v[124:125]
	v_pk_mul_f32 v[28:29], v[28:29], v[112:113]
	v_pk_mul_f32 v[24:25], v[24:25], v[116:117]
	v_pk_mul_f32 v[20:21], v[20:21], v[120:121]
	v_pk_mul_f32 v[30:31], v[30:31], v[114:115]
	v_pk_mul_f32 v[26:27], v[26:27], v[118:119]
	v_pk_mul_f32 v[22:23], v[22:23], v[122:123]
	v_pk_mul_f32 v[18:19], v[18:19], v[126:127]
	v_pk_mul_f32 v[16:17], v[16:17], v[124:125]
	v_pk_mul_f32 v[12:13], v[12:13], v[112:113]
	v_pk_mul_f32 v[8:9], v[8:9], v[116:117]
	v_pk_mul_f32 v[4:5], v[4:5], v[120:121]
	v_pk_mul_f32 v[14:15], v[14:15], v[114:115]
	v_pk_mul_f32 v[10:11], v[10:11], v[118:119]
	v_pk_mul_f32 v[6:7], v[6:7], v[122:123]
	v_pk_mul_f32 v[2:3], v[2:3], v[126:127]
	v_pk_mul_f32 v[0:1], v[0:1], v[124:125]
